# static priority raise (s_setprio 1) for waves 4-7 across the attention phases, reset at the phase exit
# speedup vs baseline: 1.0017x; 1.0017x over previous
.LBB0_941:
	s_or_b64 exec, exec, s[0:1]
	s_mov_b32 s22, s83
	s_mov_b32 s94, s90
	s_mov_b64 s[0:1], s[96:97]
	s_mov_b32 s95, s92
	s_waitcnt lgkmcnt(0)
	s_barrier
	v_mov_b32_e32 v2, v202
	s_cmpk_gt_i32 s94, 0x1ff
	s_cbranch_scc1 .LBB0_1002
	s_load_dwordx2 s[0:1], s[0:1], 0xa0
	v_and_b32_e32 v11, 7, v2
	v_lshlrev_b32_e32 v0, 4, v11
	v_mov_b32_e32 v1, 0
	s_mov_b64 s[4:5], 0x800000
	s_waitcnt lgkmcnt(0)
	s_add_u32 s82, s0, 0x8600000
	s_addc_u32 s83, s1, 0
	s_add_u32 s84, s0, 0x11000000
	s_addc_u32 s85, s1, 0
	s_lshl_b32 s2, s22, 5
	v_lshl_add_u64 v[4:5], s[0:1], 0, v[0:1]
	s_ashr_i32 s96, s22, 1
	v_ashrrev_i32_e32 v9, 5, v2
	s_and_b32 s2, s2, 32
	v_lshl_add_u64 v[112:113], v[4:5], 0, s[4:5]
	s_mov_b64 s[4:5], 0x880000
	v_lshl_add_u64 v[114:115], v[4:5], 0, s[4:5]
	s_add_u32 s4, s0, 0x9600000
	v_lshlrev_b32_e32 v116, 3, v9
	v_lshlrev_b32_e32 v136, 4, v9
	v_lshlrev_b32_e32 v118, 2, v9
	v_and_b32_e32 v9, 64, v202
	v_lshlrev_b32_e32 v200, 2, v11
	v_writelane_b32 v254, s4, 15
	s_addc_u32 s4, s1, 0
	v_add_u32_e32 v9, 64, v9
	v_xor_b32_e32 v18, 32, v202
	v_or_b32_e32 v215, 2, v200
	v_writelane_b32 v254, s4, 17
	v_cmp_lt_i32_e32 vcc, v18, v9
	s_lshl_b32 s4, s96, 6
	v_cmp_lt_u32_e64 s[24:25], 5, v215
	v_lshlrev_b32_e32 v3, 2, v2
	v_lshl_add_u32 v8, s22, 6, v2
	v_and_b32_e32 v14, 31, v2
	v_and_b32_e32 v15, 16, v2
	v_cndmask_b32_e32 v18, v202, v18, vcc
	s_or_b32 s4, s4, s2
	v_writelane_b32 v254, s24, 19
	v_add_u32_e32 v123, 0, v0
	v_ashrrev_i32_e32 v0, 3, v8
	v_lshlrev_b32_e32 v196, 2, v18
	v_or_b32_e32 v18, s4, v14
	s_movk_i32 s7, 0x84
	v_and_or_b32 v15, v3, 12, v15
	v_writelane_b32 v254, s25, 20
	v_cmp_lt_u32_e64 s[24:25], 9, v215
	v_mul_lo_u32 v18, v18, s7
	v_lshlrev_b32_e32 v198, 1, v15
	v_lshl_add_u32 v15, v0, 5, v0
	v_writelane_b32 v254, s24, 21
	v_add3_u32 v197, 0, v18, v118
	v_add_u32_e32 v18, v15, v200
	s_add_i32 s8, 0, 0x18000
	v_or_b32_e32 v213, 1, v200
	v_writelane_b32 v254, s25, 22
	v_cmp_lt_u32_e64 s[24:25], 13, v215
	v_lshrrev_b32_e32 v10, 2, v2
	v_add_u32_e32 v6, 0x200, v8
	v_lshl_add_u32 v212, v18, 2, s8
	v_add_u32_e32 v18, v15, v213
	v_or_b32_e32 v217, 3, v200
	v_writelane_b32 v254, s24, 23
	s_movk_i32 s23, 0x90
	s_movk_i32 s6, 0xc0
	v_ashrrev_i32_e32 v12, 3, v6
	v_and_or_b32 v10, v10, 3, v118
	v_lshl_add_u32 v214, v18, 2, s8
	v_add_u32_e32 v18, v15, v215
	v_add_u32_e32 v15, v15, v217
	v_writelane_b32 v254, s25, 24
	v_cmp_lt_u32_e64 s[24:25], 17, v215
	v_cmp_lt_i32_e32 vcc, v208, v9
	v_mul_lo_u32 v135, v0, s6
	v_lshlrev_b32_e32 v6, 6, v12
	v_mul_lo_u32 v13, v12, s23
	v_mul_lo_u32 v12, v12, s6
	v_mul_lo_u32 v10, v10, s6
	v_mul_lo_u32 v201, v0, s7
	v_cmp_eq_u32_e64 s[6:7], 0, v11
	v_lshl_add_u32 v216, v18, 2, s8
	v_lshl_add_u32 v218, v15, 2, s8
	v_cmp_ne_u32_e64 s[8:9], 0, v11
	v_cmp_lt_u32_e64 s[10:11], 1, v11
	v_cmp_lt_u32_e64 s[12:13], 2, v11
	v_cmp_lt_u32_e64 s[14:15], 3, v11
	v_cmp_lt_u32_e64 s[16:17], 4, v11
	v_cmp_lt_u32_e64 s[18:19], 5, v11
	v_cmp_eq_u32_e64 s[20:21], 7, v11
	v_writelane_b32 v254, s24, 25
	v_cndmask_b32_e32 v11, v202, v208, vcc
	v_cmp_lt_i32_e32 vcc, v203, v9
	s_lshl_b32 s22, s22, 13
	v_writelane_b32 v254, s25, 26
	v_lshlrev_b32_e32 v219, 2, v11
	v_cndmask_b32_e32 v11, v202, v203, vcc
	v_cmp_lt_i32_e32 vcc, v209, v9
	s_add_i32 s24, 0, 0x1a100
	s_lshl_b32 s25, s2, 2
	s_add_i32 s22, s22, 0
	v_lshlrev_b32_e32 v220, 2, v11
	v_cndmask_b32_e32 v11, v202, v209, vcc
	v_lshl_add_u32 v222, v0, 2, s24
	v_lshl_add_u32 v223, v8, 2, s24
	s_add_i32 s24, s24, s25
	v_add_u32_e32 v227, s22, v3
	s_movk_i32 s22, 0x300
	v_lshlrev_b32_e32 v221, 2, v11
	v_xor_b32_e32 v11, 8, v202
	v_lshl_add_u32 v226, v14, 2, s24
	v_mul_lo_u32 v3, v0, s22
	s_add_i32 s22, 0, 0x1a400
	s_add_i32 s24, 0, 0x1c800
	v_cmp_lt_i32_e32 vcc, v11, v9
	v_xor_b32_e32 v15, 16, v202
	s_add_u32 s86, s0, 0x6600000
	v_mul_lo_u32 v134, v0, s23
	v_cndmask_b32_e32 v11, v202, v11, vcc
	v_cmp_lt_i32_e32 vcc, v15, v9
	v_cmp_gt_i32_e64 s[76:77], 64, v8
	s_addc_u32 s87, s1, 0
	v_cmp_eq_u32_e64 s[0:1], 0, v8
	v_lshlrev_b32_e32 v8, 3, v2
	v_lshlrev_b32_e32 v4, 6, v0
	v_cmp_gt_u32_e64 s[4:5], 32, v2
	v_cndmask_b32_e32 v9, v202, v15, vcc
	v_writelane_b32 v254, s0, 27
	v_and_or_b32 v3, v8, 56, v3
	v_add_u32_e32 v122, 0, v134
	v_lshlrev_b32_e32 v2, 4, v2
	v_ashrrev_i32_e32 v5, 31, v4
	v_ashrrev_i32_e32 v7, 31, v6
	v_add_u32_e32 v16, 0, v136
	v_mul_u32_u24_e32 v17, 0x90, v14
	v_add_u32_e32 v210, v123, v201
	v_lshlrev_b32_e32 v224, 2, v11
	v_lshlrev_b32_e32 v225, 2, v9
	v_add_u32_e32 v9, s22, v134
	v_mad_u32_u24 v11, v14, s23, 0
	v_mov_b32_e32 v15, s22
	v_writelane_b32 v254, s1, 28
	v_lshlrev_b32_e32 v120, 1, v3
	v_and_b32_e32 v229, 0x70, v2
	v_mad_u64_u32 v[2:3], s[0:1], v0, 48, v[122:123]
	v_add_u32_e32 v0, s24, v135
	s_mov_b32 s3, 0
	v_ashrrev_i32_e32 v117, 31, v116
	v_or_b32_e32 v137, 2, v118
	v_or_b32_e32 v138, 3, v118
	v_add_u32_e32 v139, 8, v118
	v_add_u32_e32 v140, 9, v118
	v_add_u32_e32 v141, 10, v118
	v_add_u32_e32 v142, 11, v118
	v_add_u32_e32 v143, 16, v118
	v_add_u32_e32 v144, 17, v118
	v_add_u32_e32 v145, 18, v118
	v_add_u32_e32 v146, 19, v118
	v_add_u32_e32 v147, 24, v118
	v_add_u32_e32 v148, 25, v118
	v_add_u32_e32 v149, 26, v118
	v_add_u32_e32 v150, 27, v118
	v_add_u32_e32 v151, 32, v118
	v_add_u32_e32 v152, 34, v118
	v_add_u32_e32 v153, 35, v118
	v_add_u32_e32 v154, 40, v118
	v_add_u32_e32 v155, 41, v118
	v_add_u32_e32 v156, 42, v118
	v_add_u32_e32 v157, 43, v118
	v_add_u32_e32 v158, 48, v118
	v_add_u32_e32 v159, 49, v118
	v_add_u32_e32 v160, 50, v118
	v_add_u32_e32 v161, 51, v118
	v_add_u32_e32 v162, 56, v118
	v_add_u32_e32 v163, 57, v118
	v_add_u32_e32 v164, 58, v118
	v_add_u32_e32 v165, 59, v118
	v_add_u32_e32 v166, 64, v118
	v_add_u32_e32 v167, 0x42, v118
	v_add_u32_e32 v168, 0x43, v118
	v_add_u32_e32 v169, 0x48, v118
	v_add_u32_e32 v170, 0x49, v118
	v_add_u32_e32 v171, 0x4a, v118
	v_add_u32_e32 v172, 0x4b, v118
	v_add_u32_e32 v173, 0x50, v118
	v_add_u32_e32 v174, 0x51, v118
	v_add_u32_e32 v175, 0x52, v118
	v_add_u32_e32 v176, 0x53, v118
	v_add_u32_e32 v177, 0x58, v118
	v_add_u32_e32 v178, 0x59, v118
	v_add_u32_e32 v179, 0x5a, v118
	v_add_u32_e32 v180, 0x5b, v118
	v_add_u32_e32 v181, 0x60, v118
	v_add_u32_e32 v182, 0x62, v118
	v_add_u32_e32 v183, 0x63, v118
	v_add_u32_e32 v184, 0x68, v118
	v_add_u32_e32 v185, 0x69, v118
	v_add_u32_e32 v186, 0x6a, v118
	v_add_u32_e32 v187, 0x6b, v118
	v_add_u32_e32 v188, 0x70, v118
	v_add_u32_e32 v189, 0x71, v118
	v_add_u32_e32 v190, 0x72, v118
	v_add_u32_e32 v191, 0x73, v118
	v_add_u32_e32 v192, 0x78, v118
	v_add_u32_e32 v193, 0x79, v118
	v_add_u32_e32 v194, 0x7a, v118
	v_add_u32_e32 v195, 0x7b, v118
	v_add3_u32 v199, 0, v10, v198
	v_add_u32_e32 v211, 0xfc00, v210
	v_cmp_lt_u32_e64 s[30:31], 21, v215
	v_cmp_lt_u32_e64 s[34:35], 25, v215
	v_cmp_lt_u32_e64 s[36:37], 4, v217
	v_cmp_lt_u32_e64 s[38:39], 5, v217
	v_cmp_lt_u32_e64 s[40:41], 6, v217
	v_cmp_lt_u32_e64 s[42:43], 8, v217
	v_cmp_lt_u32_e64 s[44:45], 9, v217
	v_cmp_lt_u32_e64 s[46:47], 10, v217
	v_cmp_lt_u32_e64 s[48:49], 12, v217
	v_cmp_lt_u32_e64 s[50:51], 13, v217
	v_cmp_lt_u32_e64 s[52:53], 14, v217
	v_cmp_lt_u32_e64 s[54:55], 16, v217
	v_cmp_lt_u32_e64 s[56:57], 17, v217
	v_cmp_lt_u32_e64 s[58:59], 18, v217
	v_cmp_lt_u32_e64 s[60:61], 20, v217
	v_cmp_lt_u32_e64 s[62:63], 21, v217
	v_cmp_lt_u32_e64 s[64:65], 22, v217
	v_cmp_lt_u32_e64 s[66:67], 24, v217
	v_cmp_lt_u32_e64 s[68:69], 25, v217
	v_cmp_lt_u32_e64 s[70:71], 26, v217
	v_cmp_lt_u32_e64 s[72:73], 28, v217
	v_cmp_lt_u32_e64 s[74:75], 29, v217
	v_mad_u32_u24 v228, v14, s23, v15
	v_mov_b32_e32 v121, v1
	v_add_u32_e32 v230, s24, v10
	v_add_u32_e32 v231, 33, v118
	v_ashrrev_i32_e32 v119, 31, v118
	v_or_b32_e32 v232, s2, v14
	v_lshlrev_b64 v[124:125], 1, v[4:5]
	v_lshlrev_b64 v[126:127], 1, v[6:7]
	v_add_u32_e32 v233, v123, v13
	v_add_u32_e32 v234, v123, v12
	v_add_u32_e32 v235, v16, v17
	s_add_i32 s78, 0, 0x1a200
	v_mov_b32_e32 v236, 0xf149f2ca
	v_mov_b32_e32 v237, 0xc61c4000
	v_mov_b32_e32 v238, 0x461c4000
	v_add_u32_e32 v239, v2, v229
	v_add_u32_e32 v240, v9, v229
	v_add_u32_e32 v241, v0, v229
	v_add_u32_e32 v242, v11, v136
	v_readlane_b32 s32, v254, 3
	s_cmp_ge_u32 s32, 4
	s_cbranch_scc0 .Lattprio_0
	s_setprio 1
.Lattprio_0:
	s_branch .LBB0_944

.LBB0_1001:
	s_setprio 0
	v_readlane_b32 s96, v254, 9
	v_readlane_b32 s97, v254, 10
	s_load_dwordx2 s[92:93], s[96:97], 0xb0
	v_readlane_b32 s74, v254, 4
	v_readlane_b32 s90, v254, 8
	v_readlane_b32 s83, v254, 3
	v_readlane_b32 s75, v254, 5

.LBB0_2188:
	s_setprio 0
	v_readlane_b32 s96, v254, 9
	v_readlane_b32 s97, v254, 10
	s_load_dwordx2 s[92:93], s[96:97], 0xb0
	v_readlane_b32 s64, v254, 4
	v_readlane_b32 s90, v254, 8
	v_readlane_b32 s83, v254, 3
	v_readlane_b32 s65, v254, 5
